# phase 4 pass-path workgroups run hg_pass3 items first and gdn_passC items second
# baseline (speedup 1.0000x reference)
.LBB0_790:
	s_mov_b32 s2, s94
	s_cmp_gt_i32 s2, 23
	s_mov_b64 s[4:5], -1
	s_cbranch_scc0 .LBB0_816
	s_mov_b32 s2, 0
	v_writelane_b32 v247, s2, 0
.Lp4_setup:
	s_mov_b64 s[4:5], s[0:1]
	s_add_i32 s8, s94, -16
	s_cmpk_gt_i32 s8, 0x407
	s_cbranch_scc1 .LBB0_815
	s_load_dwordx4 s[16:19], s[4:5], 0xd8
	s_load_dwordx2 s[6:7], s[4:5], 0x78
	s_add_i32 s14, s8, -8
	s_add_i32 s22, s34, -24
	v_mbcnt_lo_u32_b32 v0, -1, 0
	s_waitcnt lgkmcnt(0)
	s_add_u32 s24, s18, 0x2030000
	s_addc_u32 s25, s19, 0
	s_add_u32 s30, s16, 0x3000000
	s_addc_u32 s33, s17, 0
	s_add_u32 s36, s18, 0x117b0000
	s_waitcnt vmcnt(3)
	v_mbcnt_hi_u32_b32 v28, -1, v0
	s_addc_u32 s37, s19, 0
	s_lshl_b32 s2, s8, 2
	s_lshl_b32 s3, s34, 2
	s_lshl_b32 s8, s8, 6
	s_lshl_b32 s11, s34, 6
	s_ashr_i32 s15, s14, 31
	s_ashr_i32 s23, s22, 31
	v_and_b32_e32 v0, 64, v28
	s_sub_i32 s2, s2, 32
	s_sub_i32 s3, s3, 32
	s_add_i32 s10, s8, 0xfffffe00
	s_addk_i32 s11, 0xfe00
	s_lshl_b64 s[8:9], s[14:15], 14
	s_lshl_b64 s[12:13], s[22:23], 14
	s_lshl_b64 s[26:27], s[14:15], 13
	s_lshl_b64 s[28:29], s[22:23], 13
	s_movk_i32 s15, 0x100
	v_mov_b32_e32 v17, 0
	s_mov_b32 s23, 0x127b0000
	s_mov_b32 s31, 0
	v_mov_b32_e32 v24, s37
	v_mov_b32_e32 v25, s33
	v_mov_b32_e32 v26, s36
	v_mov_b32_e32 v27, s30
	s_mov_b32 s33, 0x137b0000
	s_brev_b32 s42, 64
	s_movk_i32 s43, 0x1000
	s_movk_i32 s44, 0x2000
	s_mov_b32 s45, 0x2001000
	s_movk_i32 s46, 0x3000
	s_waitcnt vmcnt(2)
	v_xor_b32_e32 v29, 16, v28
	s_waitcnt vmcnt(1)
	v_add_u32_e32 v30, 64, v0
	v_xor_b32_e32 v31, 32, v28
	v_mov_b32_e32 v32, 0x358637bd
	s_mov_b32 s47, 0x800000
	s_movk_i32 s48, 0x3c00
	s_mov_b64 s[36:37], 0x1c00
	s_movk_i32 s49, 0x7fff
	s_movk_i32 s50, 0x110
	v_mov_b32_e32 v33, 0x3c00
	v_mov_b32_e32 v34, 1
	s_mov_b32 s51, s14
	v_readlane_b32 s2, v247, 0
	s_cmp_eq_u32 s2, 0
	s_cbranch_scc0 .LBB0_794
	v_and_b32_e32 v22, 63, v156
	v_xor_b32_e32 v23, 32, v22
	v_xor_b32_e32 v22, 16, v22
	v_lshlrev_b32_e32 v22, 2, v22
	v_lshlrev_b32_e32 v23, 2, v23
	s_branch .LBB0_796

.LBB0_796:
	v_readlane_b32 s2, v247, 0
	s_cmp_eq_u32 s2, 0
	s_cbranch_scc0 .LBB0_815
	s_sub_i32 s14, s34, s94
	s_add_i32 s14, s14, -1
	s_load_dwordx2 s[18:19], s[4:5], 0x40
	s_load_dwordx2 s[26:27], s[4:5], 0x70
	s_movk_i32 s2, 0x3c00
	s_mov_b32 s29, 0
	v_mov_b32_e32 v17, 0
	s_mov_b32 s3, 0x800000
	s_mov_b32 s10, 0x3f317217
	s_mov_b32 s11, 0x7f800000
	s_movk_i32 s23, 0x4000
	s_movk_i32 s33, 0x3000
	s_movk_i32 s42, 0x7000
	s_mov_b32 s43, 0xb000
	s_mov_b32 s44, 0xf000
	s_mov_b32 s45, 0x13000
	s_mov_b32 s46, 0x12000
	s_mov_b32 s47, 0x16000
	s_mov_b32 s48, 0x1a000
	s_mov_b32 s49, 0x1e000
	s_mov_b32 s50, 0x22000
	s_mov_b32 s51, 0x21000
	s_mov_b32 s52, 0x25000
	s_mov_b32 s53, 0x29000
	s_mov_b32 s54, 0x2d000
	s_mov_b32 s55, 0x31000
	s_mov_b32 s56, 0x30000
	s_mov_b32 s57, 0x34000
	s_mov_b32 s58, 0x38000
	s_mov_b32 s59, 0x8000
	s_mov_b32 s60, 0x17000
	s_mov_b32 s61, 0x26000
	s_mov_b32 s62, 0x35000
	s_add_i32 s63, 0, 0x19e00
	s_movk_i32 s64, 0x7fff
	s_movk_i32 s65, 0x880
	s_mov_b32 s66, 0x42a00000
	s_movk_i32 s67, 0x1100
	s_movk_i32 s68, 0x90
	s_add_i32 s69, 0, 0x13200
	s_movk_i32 s70, 0x110
	s_add_i32 s71, 0, 0x17a00
	s_mov_b32 s72, 0xffff0000
	s_add_i32 s73, 0, 0x1a600
	v_mov_b32_e32 v20, 0x358637bd
	v_mov_b32_e32 v21, 0x41b17218
	v_mov_b32_e32 v24, 1
	v_and_b32_e32 v176, 15, v156
	v_bfe_u32 v177, v156, 4, 2
	v_lshlrev_b32_e32 v177, 4, v177
	v_lshrrev_b32_e32 v178, 8, v156
	v_lshl_or_b32 v178, v178, 6, v176
	v_bfe_u32 v179, v156, 6, 2
	v_lshl_or_b32 v179, v179, 4, v176
	v_mad_u32_u24 v100, v178, s70, v177
	v_add_u32_e32 v100, 0x1a800, v100
	v_mad_u32_u24 v101, v178, s68, v177
	v_add_u32_e32 v101, 0x13200, v101
	v_mad_u32_u24 v102, v179, s68, v177
	v_add_u32_e32 v102, 0x17a00, v102
	v_mad_u32_u24 v103, v179, s70, v177
	v_add_u32_e32 v103, 0x4400, v103
	v_lshrrev_b32_e32 v96, 4, v156
	v_and_b32_e32 v97, 15, v156
	v_lshlrev_b32_e32 v97, 4, v97
	v_mad_u32_u24 v96, v96, s70, v97
	v_add_u32_e32 v96, 0x1a800, v96
	v_lshlrev_b32_e32 v97, 4, v156
	s_waitcnt lgkmcnt(0)
	s_mov_b32 s98, s14
	s_lshr_b32 s99, s98, 7
	s_lshl_b32 s99, s99, 11
	s_lshl_b32 s100, s98, 6
	s_and_b32 s100, s100, 0x7c0
	s_or_b32 s99, s99, s100
	s_lshl_b32 s100, s98, 2
	s_and_b32 s100, s100, 0x180
	v_lshrrev_b32_e32 v176, 7, v156
	v_lshl_add_u32 v176, v176, 4, s99
	v_and_b32_e32 v178, 0x7f, v156
	v_or_b32_e32 v177, s100, v178
	v_lshlrev_b32_e32 v177, 2, v177
	global_load_dword v232, v177, s[18:19] offset:2048
	global_load_dword v233, v177, s[18:19]
	s_lshl_b32 s100, s100, 1
	v_lshl_add_u32 v178, v178, 1, s100
	v_mov_b32_e32 v179, 0
	v_lshl_add_u64 v[152:153], v[178:179], 0, s[24:25]
	v_mad_u64_u32 v[152:153], vcc, v176, s2, v[152:153]
	s_lshl_b32 s100, s98, 15
	s_add_u32 s100, s16, s100
	s_addc_u32 s101, s17, 0
	global_load_dwordx4 v[160:163], v97, s[100:101]
	s_add_u32 s100, s100, 0x2000
	s_addc_u32 s101, s101, 0
	global_load_dwordx4 v[164:167], v97, s[100:101]
	s_add_u32 s100, s100, 0x2000
	s_addc_u32 s101, s101, 0
	global_load_dwordx4 v[168:171], v97, s[100:101]
	s_add_u32 s100, s100, 0x2000
	s_addc_u32 s101, s101, 0
	global_load_dwordx4 v[172:175], v97, s[100:101]
	s_mov_b32 s100, 0x3c00
	s_mov_b32 s101, 0
	global_load_ushort v104, v[152:153], off
	global_load_ushort v105, v[152:153], off offset:1024
	global_load_ushort v106, v[152:153], off offset:2048
	v_lshl_add_u64 v[154:155], v[152:153], 0, s[100:101]
	global_load_ushort v107, v[154:155], off
	global_load_ushort v108, v[154:155], off offset:1024
	global_load_ushort v109, v[154:155], off offset:2048
	v_lshl_add_u64 v[158:159], v[154:155], 0, s[100:101]
	global_load_ushort v110, v[158:159], off
	global_load_ushort v111, v[158:159], off offset:1024
	global_load_ushort v112, v[158:159], off offset:2048
	v_lshl_add_u64 v[154:155], v[158:159], 0, s[100:101]
	global_load_ushort v113, v[154:155], off
	global_load_ushort v114, v[154:155], off offset:1024
	global_load_ushort v115, v[154:155], off offset:2048
	v_lshl_add_u64 v[158:159], v[154:155], 0, s[100:101]
	global_load_ushort v116, v[158:159], off
	global_load_ushort v117, v[158:159], off offset:1024
	global_load_ushort v118, v[158:159], off offset:2048
	v_lshl_add_u64 v[154:155], v[158:159], 0, s[100:101]
	global_load_ushort v119, v[154:155], off
	global_load_ushort v120, v[154:155], off offset:1024
	global_load_ushort v121, v[154:155], off offset:2048
	v_lshl_add_u64 v[158:159], v[154:155], 0, s[100:101]
	global_load_ushort v122, v[158:159], off
	global_load_ushort v123, v[158:159], off offset:1024
	global_load_ushort v124, v[158:159], off offset:2048
	v_lshl_add_u64 v[154:155], v[158:159], 0, s[100:101]
	global_load_ushort v125, v[154:155], off
	global_load_ushort v126, v[154:155], off offset:1024
	global_load_ushort v127, v[154:155], off offset:2048
	v_lshl_add_u64 v[158:159], v[154:155], 0, s[100:101]
	global_load_ushort v128, v[158:159], off
	global_load_ushort v129, v[158:159], off offset:1024
	global_load_ushort v130, v[158:159], off offset:2048
	v_lshl_add_u64 v[154:155], v[158:159], 0, s[100:101]
	global_load_ushort v131, v[154:155], off
	global_load_ushort v132, v[154:155], off offset:1024
	global_load_ushort v133, v[154:155], off offset:2048
	v_lshl_add_u64 v[158:159], v[154:155], 0, s[100:101]
	global_load_ushort v134, v[158:159], off
	global_load_ushort v135, v[158:159], off offset:1024
	global_load_ushort v136, v[158:159], off offset:2048
	v_lshl_add_u64 v[154:155], v[158:159], 0, s[100:101]
	global_load_ushort v137, v[154:155], off
	global_load_ushort v138, v[154:155], off offset:1024
	global_load_ushort v139, v[154:155], off offset:2048
	v_lshl_add_u64 v[158:159], v[154:155], 0, s[100:101]
	global_load_ushort v140, v[158:159], off
	global_load_ushort v141, v[158:159], off offset:1024
	global_load_ushort v142, v[158:159], off offset:2048
	v_lshl_add_u64 v[154:155], v[158:159], 0, s[100:101]
	global_load_ushort v143, v[154:155], off
	global_load_ushort v144, v[154:155], off offset:1024
	global_load_ushort v145, v[154:155], off offset:2048
	v_lshl_add_u64 v[158:159], v[154:155], 0, s[100:101]
	global_load_ushort v146, v[158:159], off
	global_load_ushort v147, v[158:159], off offset:1024
	global_load_ushort v148, v[158:159], off offset:2048
	v_lshl_add_u64 v[154:155], v[158:159], 0, s[100:101]
	global_load_ushort v149, v[154:155], off
	global_load_ushort v150, v[154:155], off offset:1024
	global_load_ushort v151, v[154:155], off offset:2048
	s_branch .LBB0_798

.Lp4_again:
	s_waitcnt vmcnt(0)
	s_mov_b32 s2, 1
	v_writelane_b32 v247, s2, 0
	s_branch .Lp4_setup
